# top-k loop software-pipelined: next token's probability reads issued after the current key is built, one LDS wait per token, latency hidden behind the threshold search
# speedup vs baseline: 1.0012x; 1.0012x over previous
.LBB0_1139:
	v_cmp_eq_u32_e64 s[4:5], 0, v227
	v_cmp_eq_u32_e64 s[6:7], s68, v227
	s_or_b64 s[8:9], s[4:5], s[6:7]
	s_sub_i32 s6, 62, s74
	s_lshl_b32 s0, s72, 6
	v_cmp_eq_u32_e64 s[6:7], s6, v227
	v_lshlrev_b32_e32 v34, 4, v227
	s_add_i32 s0, s0, 64
	v_lshlrev_b32_e32 v38, 2, v227
	s_or_b64 s[6:7], s[8:9], s[6:7]
	s_movk_i32 s8, 0xff00
	v_lshl_add_u32 v42, v225, 8, 0
	v_lshl_or_b32 v44, v225, 13, v34
	v_cmp_gt_i32_e32 vcc, s0, v38
	v_xor_b32_e32 v39, 63, v227
	v_xor_b32_e32 v40, 0x7f, v227
	v_cmp_lt_i32_e64 s[0:1], s68, v227
	v_cmp_ne_u32_e64 s[2:3], 0, v227
	v_bitop3_b32 v41, v227, s8, 63 bitop3:0xde
	s_mov_b32 s12, 8
	v_add_u32_e32 v43, v42, v38
	v_add_u32_e32 v45, 0x10000, v44
	v_lshl_add_u32 v46, v225, 6, v197
	s_barrier
	v_mov_b32_e32 v37, 0
	s_and_saveexec_b64 s[8:9], vcc
	ds_read_b128 v[34:37], v45
	s_and_saveexec_b64 s[10:11], s[2:3]
	ds_read_b32 v64, v44 offset:65532
	s_or_b64 exec, exec, s[10:11]
	s_or_b64 exec, exec, s[8:9]
	s_branch .LBB0_1141
.LBB0_1140:
.LBB0_1141:
	s_waitcnt lgkmcnt(0)
	s_and_saveexec_b64 s[8:9], vcc
	v_add_f32_e32 v34, v34, v35
	v_add_f32_e32 v34, v34, v36
	v_fmac_f32_e32 v37, 2.0, v34
	s_and_saveexec_b64 s[10:11], s[2:3]
	v_add_f32_e32 v37, v37, v64
	s_or_b64 exec, exec, s[10:11]
	s_or_b64 exec, exec, s[8:9]
	v_and_b32_e32 v60, 0xffffffc0, v37
	v_add_u32_e32 v60, v60, v40
	v_cndmask_b32_e64 v60, v60, v39, s[0:1]
	v_cndmask_b32_e64 v47, v60, v41, s[6:7]
	v_add_u32_e32 v45, 0x400, v45
	v_add_u32_e32 v44, 0x400, v44
	v_mov_b32_e32 v37, 0
	s_and_saveexec_b64 s[8:9], vcc
	ds_read_b128 v[34:37], v45
	s_and_saveexec_b64 s[10:11], s[2:3]
	ds_read_b32 v64, v44 offset:65532
	s_or_b64 exec, exec, s[10:11]
	s_or_b64 exec, exec, s[8:9]
	s_mov_b32 s14, 0
	s_or_b32 s15, s14, 0x80000000
	v_cmp_le_u32_e64 s[10:11], s15, v47
	s_bcnt1_i32_b64 s8, s[10:11]
	s_cmp_eq_u32 s8, 16
	s_cbranch_scc1 .Ltk_done
	s_cmp_gt_u32 s8, 15
	s_cselect_b32 s14, s15, s14
	s_or_b32 s15, s14, 0x40000000
	v_cmp_le_u32_e64 s[10:11], s15, v47
	s_bcnt1_i32_b64 s8, s[10:11]
	s_cmp_eq_u32 s8, 16
	s_cbranch_scc1 .Ltk_done
	s_cmp_gt_u32 s8, 15
	s_cselect_b32 s14, s15, s14
	s_or_b32 s15, s14, 0x20000000
	v_cmp_le_u32_e64 s[10:11], s15, v47
	s_bcnt1_i32_b64 s8, s[10:11]
	s_cmp_eq_u32 s8, 16
	s_cbranch_scc1 .Ltk_done
	s_cmp_gt_u32 s8, 15
	s_cselect_b32 s14, s15, s14
	s_or_b32 s15, s14, 0x10000000
	v_cmp_le_u32_e64 s[10:11], s15, v47
	s_bcnt1_i32_b64 s8, s[10:11]
	s_cmp_eq_u32 s8, 16
	s_cbranch_scc1 .Ltk_done
	s_cmp_gt_u32 s8, 15
	s_cselect_b32 s14, s15, s14
	s_or_b32 s15, s14, 0x8000000
	v_cmp_le_u32_e64 s[10:11], s15, v47
	s_bcnt1_i32_b64 s8, s[10:11]
	s_cmp_eq_u32 s8, 16
	s_cbranch_scc1 .Ltk_done
	s_cmp_gt_u32 s8, 15
	s_cselect_b32 s14, s15, s14
	s_or_b32 s15, s14, 0x4000000
	v_cmp_le_u32_e64 s[10:11], s15, v47
	s_bcnt1_i32_b64 s8, s[10:11]
	s_cmp_eq_u32 s8, 16
	s_cbranch_scc1 .Ltk_done
	s_cmp_gt_u32 s8, 15
	s_cselect_b32 s14, s15, s14
	s_or_b32 s15, s14, 0x2000000
	v_cmp_le_u32_e64 s[10:11], s15, v47
	s_bcnt1_i32_b64 s8, s[10:11]
	s_cmp_eq_u32 s8, 16
	s_cbranch_scc1 .Ltk_done
	s_cmp_gt_u32 s8, 15
	s_cselect_b32 s14, s15, s14
	s_or_b32 s15, s14, 0x1000000
	v_cmp_le_u32_e64 s[10:11], s15, v47
	s_bcnt1_i32_b64 s8, s[10:11]
	s_cmp_eq_u32 s8, 16
	s_cbranch_scc1 .Ltk_done
	s_cmp_gt_u32 s8, 15
	s_cselect_b32 s14, s15, s14
	s_or_b32 s15, s14, 0x800000
	v_cmp_le_u32_e64 s[10:11], s15, v47
	s_bcnt1_i32_b64 s8, s[10:11]
	s_cmp_eq_u32 s8, 16
	s_cbranch_scc1 .Ltk_done
	s_cmp_gt_u32 s8, 15
	s_cselect_b32 s14, s15, s14
	s_or_b32 s15, s14, 0x400000
	v_cmp_le_u32_e64 s[10:11], s15, v47
	s_bcnt1_i32_b64 s8, s[10:11]
	s_cmp_eq_u32 s8, 16
	s_cbranch_scc1 .Ltk_done
	s_cmp_gt_u32 s8, 15
	s_cselect_b32 s14, s15, s14
	s_or_b32 s15, s14, 0x200000
	v_cmp_le_u32_e64 s[10:11], s15, v47
	s_bcnt1_i32_b64 s8, s[10:11]
	s_cmp_eq_u32 s8, 16
	s_cbranch_scc1 .Ltk_done
	s_cmp_gt_u32 s8, 15
	s_cselect_b32 s14, s15, s14
	s_or_b32 s15, s14, 0x100000
	v_cmp_le_u32_e64 s[10:11], s15, v47
	s_bcnt1_i32_b64 s8, s[10:11]
	s_cmp_eq_u32 s8, 16
	s_cbranch_scc1 .Ltk_done
	s_cmp_gt_u32 s8, 15
	s_cselect_b32 s14, s15, s14
	s_or_b32 s15, s14, 0x80000
	v_cmp_le_u32_e64 s[10:11], s15, v47
	s_bcnt1_i32_b64 s8, s[10:11]
	s_cmp_eq_u32 s8, 16
	s_cbranch_scc1 .Ltk_done
	s_cmp_gt_u32 s8, 15
	s_cselect_b32 s14, s15, s14
	s_or_b32 s15, s14, 0x40000
	v_cmp_le_u32_e64 s[10:11], s15, v47
	s_bcnt1_i32_b64 s8, s[10:11]
	s_cmp_eq_u32 s8, 16
	s_cbranch_scc1 .Ltk_done
	s_cmp_gt_u32 s8, 15
	s_cselect_b32 s14, s15, s14
	s_or_b32 s15, s14, 0x20000
	v_cmp_le_u32_e64 s[10:11], s15, v47
	s_bcnt1_i32_b64 s8, s[10:11]
	s_cmp_eq_u32 s8, 16
	s_cbranch_scc1 .Ltk_done
	s_cmp_gt_u32 s8, 15
	s_cselect_b32 s14, s15, s14
	s_or_b32 s15, s14, 0x10000
	v_cmp_le_u32_e64 s[10:11], s15, v47
	s_bcnt1_i32_b64 s8, s[10:11]
	s_cmp_eq_u32 s8, 16
	s_cbranch_scc1 .Ltk_done
	s_cmp_gt_u32 s8, 15
	s_cselect_b32 s14, s15, s14
	s_or_b32 s15, s14, 0x8000
	v_cmp_le_u32_e64 s[10:11], s15, v47
	s_bcnt1_i32_b64 s8, s[10:11]
	s_cmp_eq_u32 s8, 16
	s_cbranch_scc1 .Ltk_done
	s_cmp_gt_u32 s8, 15
	s_cselect_b32 s14, s15, s14
	s_or_b32 s15, s14, 0x4000
	v_cmp_le_u32_e64 s[10:11], s15, v47
	s_bcnt1_i32_b64 s8, s[10:11]
	s_cmp_eq_u32 s8, 16
	s_cbranch_scc1 .Ltk_done
	s_cmp_gt_u32 s8, 15
	s_cselect_b32 s14, s15, s14
	s_or_b32 s15, s14, 0x2000
	v_cmp_le_u32_e64 s[10:11], s15, v47
	s_bcnt1_i32_b64 s8, s[10:11]
	s_cmp_eq_u32 s8, 16
	s_cbranch_scc1 .Ltk_done
	s_cmp_gt_u32 s8, 15
	s_cselect_b32 s14, s15, s14
	s_or_b32 s15, s14, 0x1000
	v_cmp_le_u32_e64 s[10:11], s15, v47
	s_bcnt1_i32_b64 s8, s[10:11]
	s_cmp_eq_u32 s8, 16
	s_cbranch_scc1 .Ltk_done
	s_cmp_gt_u32 s8, 15
	s_cselect_b32 s14, s15, s14
	s_or_b32 s15, s14, 0x800
	v_cmp_le_u32_e64 s[10:11], s15, v47
	s_bcnt1_i32_b64 s8, s[10:11]
	s_cmp_eq_u32 s8, 16
	s_cbranch_scc1 .Ltk_done
	s_cmp_gt_u32 s8, 15
	s_cselect_b32 s14, s15, s14
	s_or_b32 s15, s14, 0x400
	v_cmp_le_u32_e64 s[10:11], s15, v47
	s_bcnt1_i32_b64 s8, s[10:11]
	s_cmp_eq_u32 s8, 16
	s_cbranch_scc1 .Ltk_done
	s_cmp_gt_u32 s8, 15
	s_cselect_b32 s14, s15, s14
	s_or_b32 s15, s14, 0x200
	v_cmp_le_u32_e64 s[10:11], s15, v47
	s_bcnt1_i32_b64 s8, s[10:11]
	s_cmp_eq_u32 s8, 16
	s_cbranch_scc1 .Ltk_done
	s_cmp_gt_u32 s8, 15
	s_cselect_b32 s14, s15, s14
	s_or_b32 s15, s14, 0x100
	v_cmp_le_u32_e64 s[10:11], s15, v47
	s_bcnt1_i32_b64 s8, s[10:11]
	s_cmp_eq_u32 s8, 16
	s_cbranch_scc1 .Ltk_done
	s_cmp_gt_u32 s8, 15
	s_cselect_b32 s14, s15, s14
	s_or_b32 s15, s14, 0x80
	v_cmp_le_u32_e64 s[10:11], s15, v47
	s_bcnt1_i32_b64 s8, s[10:11]
	s_cmp_eq_u32 s8, 16
	s_cbranch_scc1 .Ltk_done
	s_cmp_gt_u32 s8, 15
	s_cselect_b32 s14, s15, s14
	s_or_b32 s15, s14, 64
	v_cmp_le_u32_e64 s[10:11], s15, v47
	s_bcnt1_i32_b64 s8, s[10:11]
	s_cmp_eq_u32 s8, 16
	s_cbranch_scc1 .Ltk_done
	s_cmp_gt_u32 s8, 15
	s_cselect_b32 s14, s15, s14
	s_or_b32 s15, s14, 32
	v_cmp_le_u32_e64 s[10:11], s15, v47
	s_bcnt1_i32_b64 s8, s[10:11]
	s_cmp_eq_u32 s8, 16
	s_cbranch_scc1 .Ltk_done
	s_cmp_gt_u32 s8, 15
	s_cselect_b32 s14, s15, s14
	s_or_b32 s15, s14, 16
	v_cmp_le_u32_e64 s[10:11], s15, v47
	s_bcnt1_i32_b64 s8, s[10:11]
	s_cmp_eq_u32 s8, 16
	s_cbranch_scc1 .Ltk_done
	s_cmp_gt_u32 s8, 15
	s_cselect_b32 s14, s15, s14
	s_or_b32 s15, s14, 8
	v_cmp_le_u32_e64 s[10:11], s15, v47
	s_bcnt1_i32_b64 s8, s[10:11]
	s_cmp_eq_u32 s8, 16
	s_cbranch_scc1 .Ltk_done
	s_cmp_gt_u32 s8, 15
	s_cselect_b32 s14, s15, s14
	s_or_b32 s15, s14, 4
	v_cmp_le_u32_e64 s[10:11], s15, v47
	s_bcnt1_i32_b64 s8, s[10:11]
	s_cmp_eq_u32 s8, 16
	s_cbranch_scc1 .Ltk_done
	s_cmp_gt_u32 s8, 15
	s_cselect_b32 s14, s15, s14
	s_or_b32 s15, s14, 2
	v_cmp_le_u32_e64 s[10:11], s15, v47
	s_bcnt1_i32_b64 s8, s[10:11]
	s_cmp_eq_u32 s8, 16
	s_cbranch_scc1 .Ltk_done
	s_cmp_gt_u32 s8, 15
	s_cselect_b32 s14, s15, s14
	s_or_b32 s15, s14, 1
	v_cmp_le_u32_e64 s[10:11], s15, v47
	s_bcnt1_i32_b64 s8, s[10:11]
	s_cmp_eq_u32 s8, 16
	s_cbranch_scc1 .Ltk_done
	s_cmp_gt_u32 s8, 15
	s_cselect_b32 s14, s15, s14
	v_cmp_le_u32_e64 s[10:11], s14, v47
.Ltk_done:
	s_and_saveexec_b64 s[8:9], s[4:5]
	v_mov_b64_e32 v[60:61], s[10:11]
	ds_write_b64 v46, v[60:61]
	s_or_b64 exec, exec, s[8:9]
	s_add_i32 s12, s12, -1
	v_add_u32_e32 v46, 8, v46
	s_cmp_lg_u32 s12, 0
	s_cbranch_scc1 .LBB0_1141
	s_waitcnt lgkmcnt(0)
